# v65 plus three GEMM1 K-loop stage loads in saddr+voffset form (64-bit address adds dropped)
# speedup vs baseline: 1.0062x; 1.0037x over previous
.LBB0_262:
	ds_read_b128 v[128:131], v181
	ds_read_b128 v[132:135], v181 offset:1024
	ds_read_b128 v[136:139], v181 offset:2048
	ds_read_b128 v[140:143], v181 offset:3072
	s_add_u32 s6, s4, 0xfff80080
	s_addc_u32 s7, s5, -1
	s_cmp_eq_u32 s37, 28
	s_cselect_b32 s9, s10, s7
	s_cselect_b32 s8, s11, s6
	s_cselect_b32 s7, s20, s36
	s_cselect_b32 s6, s34, s35
	v_lshl_add_u64 v[176:177], s[4:5], 0, v[158:159]
	s_add_i32 m0, s44, 0xc000
	ds_read_b128 v[144:147], v182
	ds_read_b128 v[168:171], v182 offset:1024
	ds_read_b128 v[172:175], v182 offset:2048
	ds_read_b128 v[184:187], v182 offset:3072
	ds_read_b128 v[188:191], v182 offset:4096
	ds_read_b128 v[192:195], v182 offset:5120
	ds_read_b128 v[196:199], v182 offset:6144
	ds_read_b128 v[200:203], v182 offset:7168
	global_load_lds_dwordx4 v[176:177], off
	s_add_i32 m0, s44, 0xe000
	s_nop 0
	global_load_lds_dwordx4 v160, s[4:5]
	s_waitcnt lgkmcnt(8)
	s_barrier
	s_waitcnt lgkmcnt(0)
	s_waitcnt lgkmcnt(0)
	v_mfma_f32_16x16x32_bf16 v[124:127], v[128:131], v[144:147], v[124:127]
	v_mfma_f32_16x16x32_bf16 v[120:123], v[136:139], v[144:147], v[120:123]
	v_mfma_f32_16x16x32_bf16 v[108:111], v[128:131], v[172:175], v[108:111]
	v_mfma_f32_16x16x32_bf16 v[104:107], v[136:139], v[172:175], v[104:107]
	v_mfma_f32_16x16x32_bf16 v[92:95], v[128:131], v[188:191], v[92:95]
	v_mfma_f32_16x16x32_bf16 v[88:91], v[136:139], v[188:191], v[88:91]
	v_mfma_f32_16x16x32_bf16 v[76:79], v[128:131], v[196:199], v[76:79]
	v_mfma_f32_16x16x32_bf16 v[72:75], v[136:139], v[196:199], v[72:75]
	v_mfma_f32_16x16x32_bf16 v[124:127], v[132:135], v[168:171], v[124:127]
	v_mfma_f32_16x16x32_bf16 v[120:123], v[140:143], v[168:171], v[120:123]
	v_mfma_f32_16x16x32_bf16 v[108:111], v[132:135], v[184:187], v[108:111]
	v_mfma_f32_16x16x32_bf16 v[104:107], v[140:143], v[184:187], v[104:107]
	v_mfma_f32_16x16x32_bf16 v[92:95], v[132:135], v[192:195], v[92:95]
	v_mfma_f32_16x16x32_bf16 v[88:91], v[140:143], v[192:195], v[88:91]
	v_mfma_f32_16x16x32_bf16 v[76:79], v[132:135], v[200:203], v[76:79]
	v_mfma_f32_16x16x32_bf16 v[72:75], v[140:143], v[200:203], v[72:75]
	s_barrier
	s_add_i32 s39, s80, s33
	v_lshl_add_u64 v[176:177], s[6:7], 0, v[150:151]
	s_mov_b32 m0, s39
	ds_read_b128 v[204:207], v183
	ds_read_b128 v[210:213], v183 offset:1024
	ds_read_b128 v[214:217], v183 offset:2048
	ds_read_b128 v[218:221], v183 offset:3072
	global_load_lds_dwordx4 v[176:177], off
	v_lshl_add_u64 v[222:223], s[6:7], 0, v[154:155]
	s_add_i32 m0, s39, 0x2000
	s_nop 0
	global_load_lds_dwordx4 v[222:223], off
	s_barrier
	s_waitcnt lgkmcnt(0)
	s_waitcnt lgkmcnt(0)
	v_mfma_f32_16x16x32_bf16 v[116:119], v[204:207], v[144:147], v[116:119]
	v_mfma_f32_16x16x32_bf16 v[112:115], v[214:217], v[144:147], v[112:115]
	v_mfma_f32_16x16x32_bf16 v[100:103], v[204:207], v[172:175], v[100:103]
	v_mfma_f32_16x16x32_bf16 v[96:99], v[214:217], v[172:175], v[96:99]
	v_mfma_f32_16x16x32_bf16 v[84:87], v[204:207], v[188:191], v[84:87]
	v_mfma_f32_16x16x32_bf16 v[80:83], v[214:217], v[188:191], v[80:83]
	v_mfma_f32_16x16x32_bf16 v[68:71], v[204:207], v[196:199], v[68:71]
	v_mfma_f32_16x16x32_bf16 v[64:67], v[214:217], v[196:199], v[64:67]
	v_mfma_f32_16x16x32_bf16 v[116:119], v[210:213], v[168:171], v[116:119]
	v_mfma_f32_16x16x32_bf16 v[112:115], v[218:221], v[168:171], v[112:115]
	v_mfma_f32_16x16x32_bf16 v[100:103], v[210:213], v[184:187], v[100:103]
	v_mfma_f32_16x16x32_bf16 v[96:99], v[218:221], v[184:187], v[96:99]
	v_mfma_f32_16x16x32_bf16 v[84:87], v[210:213], v[192:195], v[84:87]
	v_mfma_f32_16x16x32_bf16 v[80:83], v[218:221], v[192:195], v[80:83]
	v_mfma_f32_16x16x32_bf16 v[68:71], v[210:213], v[200:203], v[68:71]
	v_mfma_f32_16x16x32_bf16 v[64:67], v[218:221], v[200:203], v[64:67]
	s_mov_b32 m0, s44
	v_lshl_add_u64 v[224:225], s[8:9], 0, v[148:149]
	s_barrier
	ds_read_b128 v[144:147], v182 offset:16384
	ds_read_b128 v[168:171], v182 offset:17408
	ds_read_b128 v[172:175], v182 offset:18432
	ds_read_b128 v[184:187], v182 offset:19456
	ds_read_b128 v[188:191], v182 offset:20480
	ds_read_b128 v[192:195], v182 offset:21504
	ds_read_b128 v[196:199], v182 offset:22528
	ds_read_b128 v[200:203], v182 offset:23552
	global_load_lds_dwordx4 v[224:225], off
	v_lshl_add_u64 v[226:227], s[8:9], 0, v[152:153]
	s_mov_b32 m0, s45
	s_nop 0
	global_load_lds_dwordx4 v[226:227], off
	s_barrier
	s_waitcnt lgkmcnt(0)
	s_waitcnt lgkmcnt(0)
	v_mfma_f32_16x16x32_bf16 v[60:63], v[128:131], v[144:147], v[60:63]
	v_mfma_f32_16x16x32_bf16 v[56:59], v[136:139], v[144:147], v[56:59]
	v_mfma_f32_16x16x32_bf16 v[44:47], v[128:131], v[172:175], v[44:47]
	v_mfma_f32_16x16x32_bf16 v[40:43], v[136:139], v[172:175], v[40:43]
	v_mfma_f32_16x16x32_bf16 v[28:31], v[128:131], v[188:191], v[28:31]
	v_mfma_f32_16x16x32_bf16 v[24:27], v[136:139], v[188:191], v[24:27]
	v_mfma_f32_16x16x32_bf16 v[12:15], v[128:131], v[196:199], v[12:15]
	v_mfma_f32_16x16x32_bf16 v[8:11], v[136:139], v[196:199], v[8:11]
	v_mfma_f32_16x16x32_bf16 v[60:63], v[132:135], v[168:171], v[60:63]
	v_mfma_f32_16x16x32_bf16 v[56:59], v[140:143], v[168:171], v[56:59]
	v_mfma_f32_16x16x32_bf16 v[44:47], v[132:135], v[184:187], v[44:47]
	v_mfma_f32_16x16x32_bf16 v[40:43], v[140:143], v[184:187], v[40:43]
	v_mfma_f32_16x16x32_bf16 v[28:31], v[132:135], v[192:195], v[28:31]
	v_mfma_f32_16x16x32_bf16 v[24:27], v[140:143], v[192:195], v[24:27]
	v_mfma_f32_16x16x32_bf16 v[12:15], v[132:135], v[200:203], v[12:15]
	v_mfma_f32_16x16x32_bf16 v[8:11], v[140:143], v[200:203], v[8:11]
	s_barrier
	s_add_u32 s78, s6, 0x80000
	s_addc_u32 s79, s7, 0
	s_add_i32 s39, s81, s33
	s_mov_b32 m0, s39
	s_nop 0
	global_load_lds_dwordx4 v150, s[78:79]
	v_lshl_add_u64 v[128:129], s[78:79], 0, v[154:155]
	s_add_i32 m0, s39, 0x2000
	s_nop 0
	global_load_lds_dwordx4 v[128:129], off
	s_waitcnt vmcnt(6)
	s_barrier
	v_mfma_f32_16x16x32_bf16 v[52:55], v[204:207], v[144:147], v[52:55]
	v_mfma_f32_16x16x32_bf16 v[48:51], v[214:217], v[144:147], v[48:51]
	v_mfma_f32_16x16x32_bf16 v[36:39], v[204:207], v[172:175], v[36:39]
	v_mfma_f32_16x16x32_bf16 v[32:35], v[214:217], v[172:175], v[32:35]
	v_mfma_f32_16x16x32_bf16 v[20:23], v[204:207], v[188:191], v[20:23]
	v_mfma_f32_16x16x32_bf16 v[16:19], v[214:217], v[188:191], v[16:19]
	v_mfma_f32_16x16x32_bf16 v[4:7], v[204:207], v[196:199], v[4:7]
	v_mfma_f32_16x16x32_bf16 v[0:3], v[214:217], v[196:199], v[0:3]
	v_mfma_f32_16x16x32_bf16 v[52:55], v[210:213], v[168:171], v[52:55]
	v_mfma_f32_16x16x32_bf16 v[48:51], v[218:221], v[168:171], v[48:51]
	v_mfma_f32_16x16x32_bf16 v[36:39], v[210:213], v[184:187], v[36:39]
	v_mfma_f32_16x16x32_bf16 v[32:35], v[218:221], v[184:187], v[32:35]
	v_mfma_f32_16x16x32_bf16 v[20:23], v[210:213], v[192:195], v[20:23]
	v_mfma_f32_16x16x32_bf16 v[16:19], v[218:221], v[192:195], v[16:19]
	v_mfma_f32_16x16x32_bf16 v[4:7], v[210:213], v[200:203], v[4:7]
	v_mfma_f32_16x16x32_bf16 v[0:3], v[218:221], v[200:203], v[0:3]
	s_add_i32 s39, 0, 0x18000
	v_add_u32_e32 v140, s39, v180
	s_barrier
	ds_read_b128 v[128:131], v140
	ds_read_b128 v[132:135], v140 offset:1024
	ds_read_b128 v[136:139], v140 offset:2048
	ds_read_b128 v[140:143], v140 offset:3072
	s_add_u32 s8, s8, 0x80000
	s_addc_u32 s9, s9, 0
	s_mov_b32 m0, s51
	v_lshl_add_u64 v[204:205], s[8:9], 0, v[148:149]
	ds_read_b128 v[144:147], v182 offset:32768
	ds_read_b128 v[168:171], v182 offset:33792
	ds_read_b128 v[172:175], v182 offset:34816
	ds_read_b128 v[184:187], v182 offset:35840
	ds_read_b128 v[188:191], v182 offset:36864
	ds_read_b128 v[192:195], v182 offset:37888
	ds_read_b128 v[196:199], v182 offset:38912
	ds_read_b128 v[200:203], v182 offset:39936
	global_load_lds_dwordx4 v[204:205], off
	v_lshl_add_u64 v[204:205], s[8:9], 0, v[152:153]
	s_mov_b32 m0, s55
	s_nop 0
	global_load_lds_dwordx4 v[204:205], off
	s_waitcnt lgkmcnt(8)
	s_barrier
	s_waitcnt lgkmcnt(0)
	s_waitcnt lgkmcnt(0)
	v_mfma_f32_16x16x32_bf16 v[124:127], v[128:131], v[144:147], v[124:127]
	v_mfma_f32_16x16x32_bf16 v[120:123], v[136:139], v[144:147], v[120:123]
	v_mfma_f32_16x16x32_bf16 v[108:111], v[128:131], v[172:175], v[108:111]
	v_mfma_f32_16x16x32_bf16 v[104:107], v[136:139], v[172:175], v[104:107]
	v_mfma_f32_16x16x32_bf16 v[92:95], v[128:131], v[188:191], v[92:95]
	v_mfma_f32_16x16x32_bf16 v[88:91], v[136:139], v[188:191], v[88:91]
	v_mfma_f32_16x16x32_bf16 v[76:79], v[128:131], v[196:199], v[76:79]
	v_mfma_f32_16x16x32_bf16 v[72:75], v[136:139], v[196:199], v[72:75]
	v_mfma_f32_16x16x32_bf16 v[124:127], v[132:135], v[168:171], v[124:127]
	v_mfma_f32_16x16x32_bf16 v[120:123], v[140:143], v[168:171], v[120:123]
	v_mfma_f32_16x16x32_bf16 v[108:111], v[132:135], v[184:187], v[108:111]
	v_mfma_f32_16x16x32_bf16 v[104:107], v[140:143], v[184:187], v[104:107]
	v_mfma_f32_16x16x32_bf16 v[92:95], v[132:135], v[192:195], v[92:95]
	v_mfma_f32_16x16x32_bf16 v[88:91], v[140:143], v[192:195], v[88:91]
	v_mfma_f32_16x16x32_bf16 v[76:79], v[132:135], v[200:203], v[76:79]
	v_mfma_f32_16x16x32_bf16 v[72:75], v[140:143], v[200:203], v[72:75]
	s_barrier
	s_add_i32 s8, 0, 0x1c000
	s_add_i32 s9, s39, s33
	v_add_u32_e32 v156, s8, v180
	v_lshl_add_u64 v[176:177], v[176:177], 0, s[24:25]
	s_mov_b32 m0, s9
	ds_read_b128 v[204:207], v156
	ds_read_b128 v[210:213], v156 offset:1024
	ds_read_b128 v[214:217], v156 offset:2048
	ds_read_b128 v[218:221], v156 offset:3072
	global_load_lds_dwordx4 v[176:177], off
	v_lshl_add_u64 v[176:177], v[222:223], 0, s[24:25]
	s_add_i32 m0, s9, 0x2000
	s_nop 0
	global_load_lds_dwordx4 v[176:177], off
	s_barrier
	s_waitcnt lgkmcnt(0)
	s_waitcnt lgkmcnt(0)
	v_mfma_f32_16x16x32_bf16 v[116:119], v[204:207], v[144:147], v[116:119]
	v_mfma_f32_16x16x32_bf16 v[112:115], v[214:217], v[144:147], v[112:115]
	v_mfma_f32_16x16x32_bf16 v[100:103], v[204:207], v[172:175], v[100:103]
	v_mfma_f32_16x16x32_bf16 v[96:99], v[214:217], v[172:175], v[96:99]
	v_mfma_f32_16x16x32_bf16 v[84:87], v[204:207], v[188:191], v[84:87]
	v_mfma_f32_16x16x32_bf16 v[80:83], v[214:217], v[188:191], v[80:83]
	v_mfma_f32_16x16x32_bf16 v[68:71], v[204:207], v[196:199], v[68:71]
	v_mfma_f32_16x16x32_bf16 v[64:67], v[214:217], v[196:199], v[64:67]
	v_mfma_f32_16x16x32_bf16 v[116:119], v[210:213], v[168:171], v[116:119]
	v_mfma_f32_16x16x32_bf16 v[112:115], v[218:221], v[168:171], v[112:115]
	v_mfma_f32_16x16x32_bf16 v[100:103], v[210:213], v[184:187], v[100:103]
	v_mfma_f32_16x16x32_bf16 v[96:99], v[218:221], v[184:187], v[96:99]
	v_mfma_f32_16x16x32_bf16 v[84:87], v[210:213], v[192:195], v[84:87]
	v_mfma_f32_16x16x32_bf16 v[80:83], v[218:221], v[192:195], v[80:83]
	v_mfma_f32_16x16x32_bf16 v[68:71], v[210:213], v[200:203], v[68:71]
	v_mfma_f32_16x16x32_bf16 v[64:67], v[218:221], v[200:203], v[64:67]
	s_mov_b32 m0, s83
	v_lshl_add_u64 v[176:177], v[224:225], 0, s[24:25]
	s_barrier
	ds_read_b128 v[144:147], v182 offset:49152
	ds_read_b128 v[168:171], v182 offset:50176
	ds_read_b128 v[172:175], v182 offset:51200
	ds_read_b128 v[184:187], v182 offset:52224
	ds_read_b128 v[188:191], v182 offset:53248
	ds_read_b128 v[192:195], v182 offset:54272
	ds_read_b128 v[196:199], v182 offset:55296
	ds_read_b128 v[200:203], v182 offset:56320
	global_load_lds_dwordx4 v[176:177], off
	v_lshl_add_u64 v[176:177], v[226:227], 0, s[24:25]
	s_mov_b32 m0, s91
	s_nop 0
	global_load_lds_dwordx4 v[176:177], off
	s_barrier
	s_waitcnt lgkmcnt(0)
	s_waitcnt lgkmcnt(0)
	v_mfma_f32_16x16x32_bf16 v[60:63], v[128:131], v[144:147], v[60:63]
	v_mfma_f32_16x16x32_bf16 v[56:59], v[136:139], v[144:147], v[56:59]
	v_mfma_f32_16x16x32_bf16 v[44:47], v[128:131], v[172:175], v[44:47]
	v_mfma_f32_16x16x32_bf16 v[40:43], v[136:139], v[172:175], v[40:43]
	v_mfma_f32_16x16x32_bf16 v[28:31], v[128:131], v[188:191], v[28:31]
	v_mfma_f32_16x16x32_bf16 v[24:27], v[136:139], v[188:191], v[24:27]
	v_mfma_f32_16x16x32_bf16 v[12:15], v[128:131], v[196:199], v[12:15]
	v_mfma_f32_16x16x32_bf16 v[8:11], v[136:139], v[196:199], v[8:11]
	v_mfma_f32_16x16x32_bf16 v[60:63], v[132:135], v[168:171], v[60:63]
	v_mfma_f32_16x16x32_bf16 v[56:59], v[140:143], v[168:171], v[56:59]
	v_mfma_f32_16x16x32_bf16 v[44:47], v[132:135], v[184:187], v[44:47]
	v_mfma_f32_16x16x32_bf16 v[40:43], v[140:143], v[184:187], v[40:43]
	v_mfma_f32_16x16x32_bf16 v[28:31], v[132:135], v[192:195], v[28:31]
	v_mfma_f32_16x16x32_bf16 v[24:27], v[140:143], v[192:195], v[24:27]
	v_mfma_f32_16x16x32_bf16 v[12:15], v[132:135], v[200:203], v[12:15]
	v_mfma_f32_16x16x32_bf16 v[8:11], v[140:143], v[200:203], v[8:11]
	s_barrier
	s_add_u32 s6, s6, 0x80080
	s_addc_u32 s7, s7, 0
	s_add_i32 s8, s8, s33
	s_mov_b32 m0, s8
	s_nop 0
	global_load_lds_dwordx4 v150, s[6:7]
	v_lshl_add_u64 v[128:129], s[6:7], 0, v[154:155]
	s_add_i32 m0, s8, 0x2000
	s_nop 0
	global_load_lds_dwordx4 v[128:129], off
	s_waitcnt vmcnt(6)
	s_barrier
	v_mfma_f32_16x16x32_bf16 v[52:55], v[204:207], v[144:147], v[52:55]
	v_mfma_f32_16x16x32_bf16 v[48:51], v[214:217], v[144:147], v[48:51]
	v_mfma_f32_16x16x32_bf16 v[36:39], v[204:207], v[172:175], v[36:39]
	v_mfma_f32_16x16x32_bf16 v[32:35], v[214:217], v[172:175], v[32:35]
	v_mfma_f32_16x16x32_bf16 v[20:23], v[204:207], v[188:191], v[20:23]
	v_mfma_f32_16x16x32_bf16 v[16:19], v[214:217], v[188:191], v[16:19]
	v_mfma_f32_16x16x32_bf16 v[4:7], v[204:207], v[196:199], v[4:7]
	v_mfma_f32_16x16x32_bf16 v[0:3], v[214:217], v[196:199], v[0:3]
	v_mfma_f32_16x16x32_bf16 v[52:55], v[210:213], v[168:171], v[52:55]
	v_mfma_f32_16x16x32_bf16 v[48:51], v[218:221], v[168:171], v[48:51]
	v_mfma_f32_16x16x32_bf16 v[36:39], v[210:213], v[184:187], v[36:39]
	v_mfma_f32_16x16x32_bf16 v[32:35], v[218:221], v[184:187], v[32:35]
	v_mfma_f32_16x16x32_bf16 v[20:23], v[210:213], v[192:195], v[20:23]
	v_mfma_f32_16x16x32_bf16 v[16:19], v[218:221], v[192:195], v[16:19]
	v_mfma_f32_16x16x32_bf16 v[4:7], v[210:213], v[200:203], v[4:7]
	v_mfma_f32_16x16x32_bf16 v[0:3], v[218:221], v[200:203], v[0:3]
	s_add_i32 s37, s37, 2
	s_add_u32 s4, s4, 0x100
	s_addc_u32 s5, s5, 0
	s_add_u32 s35, s35, 0x100
	s_addc_u32 s36, s36, 0
	s_cmp_gt_u32 s37, 29
	s_barrier
	s_cbranch_scc0 .LBB0_262
	v_mov_b32_e32 v185, v179
	v_mov_b32_e32 v184, v178
	s_cmp_lt_i32 s90, 33
	s_mov_b64 s[4:5], -1
	s_cbranch_scc0 .LBB0_589
	s_cmp_gt_i32 s82, 3
	s_cbranch_scc0 .LBB0_586
	s_cmp_gt_u32 s82, 7
	s_cbranch_scc0 .LBB0_551
	s_cmp_gt_u32 s82, 15
	s_cbranch_scc0 .LBB0_548
	s_cmp_gt_u32 s82, 23
	s_cbranch_scc0 .LBB0_545
	s_cmp_gt_u32 s82, 27
	s_cbranch_scc0 .LBB0_486
	s_cmp_gt_u32 s82, 31
	s_cbranch_scc0 .LBB0_315
	s_cmp_gt_u32 s82, 35
	s_cbranch_scc0 .LBB0_280
	s_cmp_gt_u32 s82, 39
	s_cbranch_scc0 .LBB0_277
	s_lshl_b32 s4, s90, 8
	s_add_i32 s4, s4, s57
	v_lshl_add_u32 v128, v185, 3, s59
	v_add_u32_e32 v132, s4, v184
	v_ashrrev_i32_e32 v129, 31, v128
	v_mad_i64_i32 v[130:131], s[4:5], v132, s28, 0
	s_cmp_gt_u32 s82, 41
	s_mov_b64 s[4:5], -1
	v_lshl_add_u64 v[130:131], s[0:1], 0, v[130:131]
	v_lshlrev_b64 v[128:129], 1, v[128:129]
	v_add_u32_e32 v138, 16, v132
	v_add_u32_e32 v137, 32, v132
	v_add_u32_e32 v136, 48, v132
	v_add_u32_e32 v135, 0x80, v132
	v_add_u32_e32 v134, 0x90, v132
	v_add_u32_e32 v133, 0xa0, v132
	v_add_u32_e32 v132, 0xb0, v132
	s_cbranch_scc0 .LBB0_274
	s_lshl_b32 s20, s82, 8
	s_lshl_b64 s[4:5], s[20:21], 1
	v_lshl_add_u64 v[144:145], v[130:131], 0, s[4:5]
	v_cvt_pk_bf16_f32 v140, v124, v125
	v_cvt_pk_bf16_f32 v141, v126, v127
	v_cvt_pk_bf16_f32 v142, v120, v121
	v_cvt_pk_bf16_f32 v143, v122, v123
	v_lshl_add_u64 v[144:145], v[144:145], 0, v[128:129]
	global_store_dwordx4 v[144:145], v[140:143], off
	s_nop 1
	v_cvt_pk_bf16_f32 v140, v116, v117
	v_cvt_pk_bf16_f32 v141, v118, v119
	v_cvt_pk_bf16_f32 v142, v112, v113
	v_cvt_pk_bf16_f32 v143, v114, v115
	global_store_dwordx4 v[144:145], v[140:143], off offset:256
	v_mov_b64_e32 v[144:145], s[0:1]
	v_mad_i64_i32 v[146:147], s[6:7], v138, s28, v[144:145]
	v_lshl_add_u64 v[146:147], v[146:147], 0, s[4:5]
	v_cvt_pk_bf16_f32 v140, v108, v109
	v_cvt_pk_bf16_f32 v141, v110, v111
	v_cvt_pk_bf16_f32 v142, v104, v105
	v_cvt_pk_bf16_f32 v143, v106, v107
	v_lshl_add_u64 v[146:147], v[146:147], 0, v[128:129]
	global_store_dwordx4 v[146:147], v[140:143], off
	s_nop 1
	v_cvt_pk_bf16_f32 v140, v100, v101
	v_cvt_pk_bf16_f32 v141, v102, v103
	v_cvt_pk_bf16_f32 v142, v96, v97
	v_cvt_pk_bf16_f32 v143, v98, v99
	global_store_dwordx4 v[146:147], v[140:143], off offset:256
	v_mad_i64_i32 v[146:147], s[6:7], v137, s28, v[144:145]
	v_lshl_add_u64 v[146:147], v[146:147], 0, s[4:5]
	v_cvt_pk_bf16_f32 v140, v92, v93
	v_cvt_pk_bf16_f32 v141, v94, v95
	v_cvt_pk_bf16_f32 v142, v88, v89
	v_cvt_pk_bf16_f32 v143, v90, v91
	v_lshl_add_u64 v[146:147], v[146:147], 0, v[128:129]
	global_store_dwordx4 v[146:147], v[140:143], off
	s_nop 1
	v_cvt_pk_bf16_f32 v140, v84, v85
	v_cvt_pk_bf16_f32 v141, v86, v87
	v_cvt_pk_bf16_f32 v142, v80, v81
	v_cvt_pk_bf16_f32 v143, v82, v83
	global_store_dwordx4 v[146:147], v[140:143], off offset:256
	v_mad_i64_i32 v[146:147], s[6:7], v136, s28, v[144:145]
	v_lshl_add_u64 v[146:147], v[146:147], 0, s[4:5]
	v_cvt_pk_bf16_f32 v140, v76, v77
	v_cvt_pk_bf16_f32 v141, v78, v79
	v_cvt_pk_bf16_f32 v142, v72, v73
	v_cvt_pk_bf16_f32 v143, v74, v75
	v_lshl_add_u64 v[146:147], v[146:147], 0, v[128:129]
	global_store_dwordx4 v[146:147], v[140:143], off
	s_nop 1
	v_cvt_pk_bf16_f32 v140, v68, v69
	v_cvt_pk_bf16_f32 v141, v70, v71
	v_cvt_pk_bf16_f32 v142, v64, v65
	v_cvt_pk_bf16_f32 v143, v66, v67
	global_store_dwordx4 v[146:147], v[140:143], off offset:256
	v_mad_i64_i32 v[146:147], s[6:7], v135, s28, v[144:145]
	v_lshl_add_u64 v[146:147], v[146:147], 0, s[4:5]
	v_cvt_pk_bf16_f32 v140, v60, v61
	v_cvt_pk_bf16_f32 v141, v62, v63
	v_cvt_pk_bf16_f32 v142, v56, v57
	v_cvt_pk_bf16_f32 v143, v58, v59
	v_lshl_add_u64 v[146:147], v[146:147], 0, v[128:129]
	global_store_dwordx4 v[146:147], v[140:143], off
	s_nop 1
	v_cvt_pk_bf16_f32 v140, v52, v53
	v_cvt_pk_bf16_f32 v141, v54, v55
	v_cvt_pk_bf16_f32 v142, v48, v49
	v_cvt_pk_bf16_f32 v143, v50, v51
	global_store_dwordx4 v[146:147], v[140:143], off offset:256
	v_mad_i64_i32 v[146:147], s[6:7], v134, s28, v[144:145]
	v_lshl_add_u64 v[146:147], v[146:147], 0, s[4:5]
	v_cvt_pk_bf16_f32 v140, v44, v45
	v_cvt_pk_bf16_f32 v141, v46, v47
	v_cvt_pk_bf16_f32 v142, v40, v41
	v_cvt_pk_bf16_f32 v143, v42, v43
	v_lshl_add_u64 v[146:147], v[146:147], 0, v[128:129]
	global_store_dwordx4 v[146:147], v[140:143], off
	s_nop 1
	v_cvt_pk_bf16_f32 v140, v36, v37
	v_cvt_pk_bf16_f32 v141, v38, v39
	v_cvt_pk_bf16_f32 v142, v32, v33
	v_cvt_pk_bf16_f32 v143, v34, v35
	global_store_dwordx4 v[146:147], v[140:143], off offset:256
	v_mad_i64_i32 v[146:147], s[6:7], v133, s28, v[144:145]
	v_lshl_add_u64 v[146:147], v[146:147], 0, s[4:5]
	v_cvt_pk_bf16_f32 v140, v28, v29
	v_cvt_pk_bf16_f32 v141, v30, v31
	v_cvt_pk_bf16_f32 v142, v24, v25
	v_cvt_pk_bf16_f32 v143, v26, v27
	v_lshl_add_u64 v[146:147], v[146:147], 0, v[128:129]
	v_mad_i64_i32 v[144:145], s[6:7], v132, s28, v[144:145]
	global_store_dwordx4 v[146:147], v[140:143], off
	v_lshl_add_u64 v[144:145], v[144:145], 0, s[4:5]
	v_lshl_add_u64 v[144:145], v[144:145], 0, v[128:129]
	v_cvt_pk_bf16_f32 v140, v20, v21
	v_cvt_pk_bf16_f32 v141, v22, v23
	v_cvt_pk_bf16_f32 v142, v16, v17
	v_cvt_pk_bf16_f32 v143, v18, v19
	global_store_dwordx4 v[146:147], v[140:143], off offset:256
	s_mov_b64 s[4:5], 0
	s_nop 0
	v_cvt_pk_bf16_f32 v140, v12, v13
	v_cvt_pk_bf16_f32 v141, v14, v15
	v_cvt_pk_bf16_f32 v142, v8, v9
	v_cvt_pk_bf16_f32 v143, v10, v11
	global_store_dwordx4 v[144:145], v[140:143], off
	s_nop 1
	v_cvt_pk_bf16_f32 v140, v4, v5
	v_cvt_pk_bf16_f32 v141, v6, v7
	v_cvt_pk_bf16_f32 v142, v0, v1
	v_cvt_pk_bf16_f32 v143, v2, v3
	global_store_dwordx4 v[144:145], v[140:143], off offset:256
